# prologue: composed GLA gate-weight tiles computed with all operand loads batched (16 gw + 4 rows x 16 lr per batch), pure fma chain
# speedup vs baseline: 1.0006x; 1.0006x over previous
.LBB0_70:
	s_cmp_lg_u64 s[24:25], 0
	s_cselect_b64 s[26:27], -1, 0
	s_ashr_i32 s5, s4, 31
	s_lshl_b64 s[4:5], s[4:5], 2
	s_add_u32 s4, s22, s4
	v_add_u32_e32 v10, s20, v2
	s_addc_u32 s5, s23, s5
	v_ashrrev_i32_e32 v11, 31, v10
	s_and_b64 vcc, exec, s[26:27]
	s_cbranch_vccz .LBB0_465
	v_mov_b32_e32 v8, v4
	global_load_dword v132, v8, s[24:25]
	global_load_dword v133, v8, s[24:25] offset:1024
	global_load_dword v134, v8, s[24:25] offset:2048
	global_load_dword v135, v8, s[24:25] offset:3072
	v_add_u32_e32 v8, 0x1000, v8
	global_load_dword v136, v8, s[24:25]
	global_load_dword v137, v8, s[24:25] offset:1024
	global_load_dword v138, v8, s[24:25] offset:2048
	global_load_dword v139, v8, s[24:25] offset:3072
	v_add_u32_e32 v8, 0x1000, v8
	global_load_dword v140, v8, s[24:25]
	global_load_dword v141, v8, s[24:25] offset:1024
	global_load_dword v142, v8, s[24:25] offset:2048
	global_load_dword v143, v8, s[24:25] offset:3072
	v_add_u32_e32 v8, 0x1000, v8
	global_load_dword v144, v8, s[24:25]
	global_load_dword v145, v8, s[24:25] offset:1024
	global_load_dword v146, v8, s[24:25] offset:2048
	global_load_dword v147, v8, s[24:25] offset:3072
	v_lshlrev_b32_e32 v9, 2, v10
	global_load_dwordx4 v[72:75], v9, s[16:17]
	global_load_dwordx4 v[76:79], v9, s[16:17] offset:16
	v_mul_lo_u32 v8, v10, s65
	v_add_u32_e32 v8, 0x3800, v8
	global_load_dwordx4 v[148:151], v8, s[22:23]
	global_load_dwordx4 v[152:155], v8, s[22:23] offset:16
	global_load_dwordx4 v[156:159], v8, s[22:23] offset:32
	global_load_dwordx4 v[160:163], v8, s[22:23] offset:48
	v_add_u32_e32 v8, s65, v8
	global_load_dwordx4 v[164:167], v8, s[22:23]
	global_load_dwordx4 v[168:171], v8, s[22:23] offset:16
	global_load_dwordx4 v[172:175], v8, s[22:23] offset:32
	global_load_dwordx4 v[176:179], v8, s[22:23] offset:48
	v_add_u32_e32 v8, s65, v8
	global_load_dwordx4 v[180:183], v8, s[22:23]
	global_load_dwordx4 v[184:187], v8, s[22:23] offset:16
	global_load_dwordx4 v[188:191], v8, s[22:23] offset:32
	global_load_dwordx4 v[192:195], v8, s[22:23] offset:48
	v_add_u32_e32 v8, s65, v8
	global_load_dwordx4 v[196:199], v8, s[22:23]
	global_load_dwordx4 v[200:203], v8, s[22:23] offset:16
	global_load_dwordx4 v[204:207], v8, s[22:23] offset:32
	global_load_dwordx4 v[208:211], v8, s[22:23] offset:48
	v_add_u32_e32 v8, s65, v8
	s_waitcnt vmcnt(0)
	v_fma_f32 v64, v148, v132, 0
	v_fmac_f32_e32 v64, v149, v133
	v_fmac_f32_e32 v64, v150, v134
	v_fmac_f32_e32 v64, v151, v135
	v_fmac_f32_e32 v64, v152, v136
	v_fmac_f32_e32 v64, v153, v137
	v_fmac_f32_e32 v64, v154, v138
	v_fmac_f32_e32 v64, v155, v139
	v_fmac_f32_e32 v64, v156, v140
	v_fmac_f32_e32 v64, v157, v141
	v_fmac_f32_e32 v64, v158, v142
	v_fmac_f32_e32 v64, v159, v143
	v_fmac_f32_e32 v64, v160, v144
	v_fmac_f32_e32 v64, v161, v145
	v_fmac_f32_e32 v64, v162, v146
	v_fmac_f32_e32 v64, v163, v147
	v_fma_f32 v65, v164, v132, 0
	v_fmac_f32_e32 v65, v165, v133
	v_fmac_f32_e32 v65, v166, v134
	v_fmac_f32_e32 v65, v167, v135
	v_fmac_f32_e32 v65, v168, v136
	v_fmac_f32_e32 v65, v169, v137
	v_fmac_f32_e32 v65, v170, v138
	v_fmac_f32_e32 v65, v171, v139
	v_fmac_f32_e32 v65, v172, v140
	v_fmac_f32_e32 v65, v173, v141
	v_fmac_f32_e32 v65, v174, v142
	v_fmac_f32_e32 v65, v175, v143
	v_fmac_f32_e32 v65, v176, v144
	v_fmac_f32_e32 v65, v177, v145
	v_fmac_f32_e32 v65, v178, v146
	v_fmac_f32_e32 v65, v179, v147
	v_fma_f32 v66, v180, v132, 0
	v_fmac_f32_e32 v66, v181, v133
	v_fmac_f32_e32 v66, v182, v134
	v_fmac_f32_e32 v66, v183, v135
	v_fmac_f32_e32 v66, v184, v136
	v_fmac_f32_e32 v66, v185, v137
	v_fmac_f32_e32 v66, v186, v138
	v_fmac_f32_e32 v66, v187, v139
	v_fmac_f32_e32 v66, v188, v140
	v_fmac_f32_e32 v66, v189, v141
	v_fmac_f32_e32 v66, v190, v142
	v_fmac_f32_e32 v66, v191, v143
	v_fmac_f32_e32 v66, v192, v144
	v_fmac_f32_e32 v66, v193, v145
	v_fmac_f32_e32 v66, v194, v146
	v_fmac_f32_e32 v66, v195, v147
	v_fma_f32 v67, v196, v132, 0
	v_fmac_f32_e32 v67, v197, v133
	v_fmac_f32_e32 v67, v198, v134
	v_fmac_f32_e32 v67, v199, v135
	v_fmac_f32_e32 v67, v200, v136
	v_fmac_f32_e32 v67, v201, v137
	v_fmac_f32_e32 v67, v202, v138
	v_fmac_f32_e32 v67, v203, v139
	v_fmac_f32_e32 v67, v204, v140
	v_fmac_f32_e32 v67, v205, v141
	v_fmac_f32_e32 v67, v206, v142
	v_fmac_f32_e32 v67, v207, v143
	v_fmac_f32_e32 v67, v208, v144
	v_fmac_f32_e32 v67, v209, v145
	v_fmac_f32_e32 v67, v210, v146
	v_fmac_f32_e32 v67, v211, v147
	global_load_dwordx4 v[148:151], v8, s[22:23]
	global_load_dwordx4 v[152:155], v8, s[22:23] offset:16
	global_load_dwordx4 v[156:159], v8, s[22:23] offset:32
	global_load_dwordx4 v[160:163], v8, s[22:23] offset:48
	v_add_u32_e32 v8, s65, v8
	global_load_dwordx4 v[164:167], v8, s[22:23]
	global_load_dwordx4 v[168:171], v8, s[22:23] offset:16
	global_load_dwordx4 v[172:175], v8, s[22:23] offset:32
	global_load_dwordx4 v[176:179], v8, s[22:23] offset:48
	v_add_u32_e32 v8, s65, v8
	global_load_dwordx4 v[180:183], v8, s[22:23]
	global_load_dwordx4 v[184:187], v8, s[22:23] offset:16
	global_load_dwordx4 v[188:191], v8, s[22:23] offset:32
	global_load_dwordx4 v[192:195], v8, s[22:23] offset:48
	v_add_u32_e32 v8, s65, v8
	global_load_dwordx4 v[196:199], v8, s[22:23]
	global_load_dwordx4 v[200:203], v8, s[22:23] offset:16
	global_load_dwordx4 v[204:207], v8, s[22:23] offset:32
	global_load_dwordx4 v[208:211], v8, s[22:23] offset:48
	v_add_u32_e32 v8, s65, v8
	s_waitcnt vmcnt(0)
	v_fma_f32 v68, v148, v132, 0
	v_fmac_f32_e32 v68, v149, v133
	v_fmac_f32_e32 v68, v150, v134
	v_fmac_f32_e32 v68, v151, v135
	v_fmac_f32_e32 v68, v152, v136
	v_fmac_f32_e32 v68, v153, v137
	v_fmac_f32_e32 v68, v154, v138
	v_fmac_f32_e32 v68, v155, v139
	v_fmac_f32_e32 v68, v156, v140
	v_fmac_f32_e32 v68, v157, v141
	v_fmac_f32_e32 v68, v158, v142
	v_fmac_f32_e32 v68, v159, v143
	v_fmac_f32_e32 v68, v160, v144
	v_fmac_f32_e32 v68, v161, v145
	v_fmac_f32_e32 v68, v162, v146
	v_fmac_f32_e32 v68, v163, v147
	v_fma_f32 v69, v164, v132, 0
	v_fmac_f32_e32 v69, v165, v133
	v_fmac_f32_e32 v69, v166, v134
	v_fmac_f32_e32 v69, v167, v135
	v_fmac_f32_e32 v69, v168, v136
	v_fmac_f32_e32 v69, v169, v137
	v_fmac_f32_e32 v69, v170, v138
	v_fmac_f32_e32 v69, v171, v139
	v_fmac_f32_e32 v69, v172, v140
	v_fmac_f32_e32 v69, v173, v141
	v_fmac_f32_e32 v69, v174, v142
	v_fmac_f32_e32 v69, v175, v143
	v_fmac_f32_e32 v69, v176, v144
	v_fmac_f32_e32 v69, v177, v145
	v_fmac_f32_e32 v69, v178, v146
	v_fmac_f32_e32 v69, v179, v147
	v_fma_f32 v70, v180, v132, 0
	v_fmac_f32_e32 v70, v181, v133
	v_fmac_f32_e32 v70, v182, v134
	v_fmac_f32_e32 v70, v183, v135
	v_fmac_f32_e32 v70, v184, v136
	v_fmac_f32_e32 v70, v185, v137
	v_fmac_f32_e32 v70, v186, v138
	v_fmac_f32_e32 v70, v187, v139
	v_fmac_f32_e32 v70, v188, v140
	v_fmac_f32_e32 v70, v189, v141
	v_fmac_f32_e32 v70, v190, v142
	v_fmac_f32_e32 v70, v191, v143
	v_fmac_f32_e32 v70, v192, v144
	v_fmac_f32_e32 v70, v193, v145
	v_fmac_f32_e32 v70, v194, v146
	v_fmac_f32_e32 v70, v195, v147
	v_fma_f32 v71, v196, v132, 0
	v_fmac_f32_e32 v71, v197, v133
	v_fmac_f32_e32 v71, v198, v134
	v_fmac_f32_e32 v71, v199, v135
	v_fmac_f32_e32 v71, v200, v136
	v_fmac_f32_e32 v71, v201, v137
	v_fmac_f32_e32 v71, v202, v138
	v_fmac_f32_e32 v71, v203, v139
	v_fmac_f32_e32 v71, v204, v140
	v_fmac_f32_e32 v71, v205, v141
	v_fmac_f32_e32 v71, v206, v142
	v_fmac_f32_e32 v71, v207, v143
	v_fmac_f32_e32 v71, v208, v144
	v_fmac_f32_e32 v71, v209, v145
	v_fmac_f32_e32 v71, v210, v146
	v_fmac_f32_e32 v71, v211, v147
	s_bitset1_b32 s90, 0
	s_bitset1_b32 s90, 4
	s_cmpk_lt_i32 s31, 0x1a7f
	s_cselect_b64 s[16:17], -1, 0
	s_cmpk_gt_i32 s31, 0x1a7e
	s_cbranch_scc1 .LBB0_414
	s_branch .Lpro_c0
	v_mov_b64_e32 v[8:9], s[22:23]
	v_mad_i64_i32 v[8:9], s[6:7], v10, s65, v[8:9]
	v_lshl_add_u64 v[34:35], v[8:9], 0, s[10:11]
	v_add_co_u32_e32 v8, vcc, 0x3000, v8
	s_nop 1
	v_addc_co_u32_e32 v9, vcc, 0, v9, vcc
	global_load_dwordx4 v[22:25], v[8:9], off offset:2048
	global_load_dwordx4 v[26:29], v[34:35], off offset:48
	global_load_dwordx4 v[30:33], v[34:35], off offset:32
	s_nop 0
	global_load_dwordx4 v[34:37], v[34:35], off offset:16
	v_lshl_add_u64 v[8:9], s[24:25], 0, v[4:5]
	v_add_co_u32_e32 v38, vcc, s67, v8
	s_nop 1
	v_addc_co_u32_e32 v39, vcc, 0, v9, vcc
	v_add_co_u32_e32 v40, vcc, s84, v8
	s_nop 1
	v_addc_co_u32_e32 v41, vcc, 0, v9, vcc
	v_add_co_u32_e32 v8, vcc, s66, v8
	global_load_dword v42, v[40:41], off offset:-4096
	global_load_dword v44, v[40:41], off
	global_load_dword v45, v[40:41], off offset:1024
	global_load_dword v46, v[40:41], off offset:2048
	global_load_dword v47, v[40:41], off offset:3072
	v_addc_co_u32_e32 v9, vcc, 0, v9, vcc
	global_load_dword v43, v[38:39], off offset:1024
	global_load_dword v40, v[38:39], off offset:2048
	global_load_dword v41, v[38:39], off offset:3072
	global_load_dword v7, v4, s[24:25]
	s_nop 0
	global_load_dword v38, v[8:9], off
	global_load_dword v39, v[8:9], off offset:1024
	global_load_dword v48, v[8:9], off offset:2048
	global_load_dword v49, v[8:9], off offset:3072
	global_load_dword v50, v4, s[24:25] offset:1024
	global_load_dword v51, v4, s[24:25] offset:2048
	global_load_dword v52, v4, s[24:25] offset:3072
	s_waitcnt vmcnt(7)
	v_fma_f32 v7, v22, v7, 0
	v_pk_mul_f32 v[8:9], v[34:35], v[42:43]
	v_pk_mul_f32 v[34:35], v[36:37], v[40:41]
	v_pk_mul_f32 v[30:31], v[30:31], v[44:45]
	v_pk_mul_f32 v[32:33], v[32:33], v[46:47]
	s_waitcnt vmcnt(2)
	v_fmac_f32_e32 v7, v23, v50
	s_waitcnt vmcnt(1)
	v_fmac_f32_e32 v7, v24, v51
	s_waitcnt vmcnt(0)
	v_fmac_f32_e32 v7, v25, v52
	v_add_f32_e32 v7, v7, v8
	v_add_f32_e32 v7, v7, v9
	v_add_f32_e32 v7, v7, v34
	v_add_f32_e32 v7, v7, v35
	v_add_f32_e32 v7, v7, v30
	v_add_f32_e32 v7, v7, v31
	v_add_f32_e32 v7, v7, v32
	v_pk_mul_f32 v[26:27], v[26:27], v[38:39]
	v_add_f32_e32 v7, v7, v33
	v_add_f32_e32 v7, v7, v26
	v_pk_mul_f32 v[28:29], v[28:29], v[48:49]
	v_add_f32_e32 v7, v7, v27
	v_add_f32_e32 v7, v7, v28
	v_add_f32_e32 v7, v7, v29
	v_lshl_add_u64 v[8:9], s[4:5], 0, v[4:5]
	s_cbranch_execnz .LBB0_73

.LBB0_171:
	s_cmp_lg_u64 s[26:27], 0
	s_cselect_b64 s[4:5], -1, 0
	s_ashr_i32 s7, s6, 31
	s_lshl_b64 s[6:7], s[6:7], 2
	s_add_u32 s6, s24, s6
	s_addc_u32 s7, s25, s7
	v_add_u32_e32 v10, s22, v2
	s_cmp_eq_u64 s[26:27], 0
	v_ashrrev_i32_e32 v11, 31, v10
	s_cbranch_scc1 .LBB0_473
	v_mov_b32_e32 v8, v4
	global_load_dword v132, v8, s[26:27]
	global_load_dword v133, v8, s[26:27] offset:1024
	global_load_dword v134, v8, s[26:27] offset:2048
	global_load_dword v135, v8, s[26:27] offset:3072
	v_add_u32_e32 v8, 0x1000, v8
	global_load_dword v136, v8, s[26:27]
	global_load_dword v137, v8, s[26:27] offset:1024
	global_load_dword v138, v8, s[26:27] offset:2048
	global_load_dword v139, v8, s[26:27] offset:3072
	v_add_u32_e32 v8, 0x1000, v8
	global_load_dword v140, v8, s[26:27]
	global_load_dword v141, v8, s[26:27] offset:1024
	global_load_dword v142, v8, s[26:27] offset:2048
	global_load_dword v143, v8, s[26:27] offset:3072
	v_add_u32_e32 v8, 0x1000, v8
	global_load_dword v144, v8, s[26:27]
	global_load_dword v145, v8, s[26:27] offset:1024
	global_load_dword v146, v8, s[26:27] offset:2048
	global_load_dword v147, v8, s[26:27] offset:3072
	v_lshlrev_b32_e32 v9, 2, v10
	global_load_dwordx4 v[88:91], v9, s[18:19]
	global_load_dwordx4 v[92:95], v9, s[18:19] offset:16
	v_mul_lo_u32 v8, v10, s65
	v_add_u32_e32 v8, 0x3800, v8
	global_load_dwordx4 v[148:151], v8, s[24:25]
	global_load_dwordx4 v[152:155], v8, s[24:25] offset:16
	global_load_dwordx4 v[156:159], v8, s[24:25] offset:32
	global_load_dwordx4 v[160:163], v8, s[24:25] offset:48
	v_add_u32_e32 v8, s65, v8
	global_load_dwordx4 v[164:167], v8, s[24:25]
	global_load_dwordx4 v[168:171], v8, s[24:25] offset:16
	global_load_dwordx4 v[172:175], v8, s[24:25] offset:32
	global_load_dwordx4 v[176:179], v8, s[24:25] offset:48
	v_add_u32_e32 v8, s65, v8
	global_load_dwordx4 v[180:183], v8, s[24:25]
	global_load_dwordx4 v[184:187], v8, s[24:25] offset:16
	global_load_dwordx4 v[188:191], v8, s[24:25] offset:32
	global_load_dwordx4 v[192:195], v8, s[24:25] offset:48
	v_add_u32_e32 v8, s65, v8
	global_load_dwordx4 v[196:199], v8, s[24:25]
	global_load_dwordx4 v[200:203], v8, s[24:25] offset:16
	global_load_dwordx4 v[204:207], v8, s[24:25] offset:32
	global_load_dwordx4 v[208:211], v8, s[24:25] offset:48
	v_add_u32_e32 v8, s65, v8
	s_waitcnt vmcnt(0)
	v_fma_f32 v80, v148, v132, 0
	v_fmac_f32_e32 v80, v149, v133
	v_fmac_f32_e32 v80, v150, v134
	v_fmac_f32_e32 v80, v151, v135
	v_fmac_f32_e32 v80, v152, v136
	v_fmac_f32_e32 v80, v153, v137
	v_fmac_f32_e32 v80, v154, v138
	v_fmac_f32_e32 v80, v155, v139
	v_fmac_f32_e32 v80, v156, v140
	v_fmac_f32_e32 v80, v157, v141
	v_fmac_f32_e32 v80, v158, v142
	v_fmac_f32_e32 v80, v159, v143
	v_fmac_f32_e32 v80, v160, v144
	v_fmac_f32_e32 v80, v161, v145
	v_fmac_f32_e32 v80, v162, v146
	v_fmac_f32_e32 v80, v163, v147
	v_fma_f32 v81, v164, v132, 0
	v_fmac_f32_e32 v81, v165, v133
	v_fmac_f32_e32 v81, v166, v134
	v_fmac_f32_e32 v81, v167, v135
	v_fmac_f32_e32 v81, v168, v136
	v_fmac_f32_e32 v81, v169, v137
	v_fmac_f32_e32 v81, v170, v138
	v_fmac_f32_e32 v81, v171, v139
	v_fmac_f32_e32 v81, v172, v140
	v_fmac_f32_e32 v81, v173, v141
	v_fmac_f32_e32 v81, v174, v142
	v_fmac_f32_e32 v81, v175, v143
	v_fmac_f32_e32 v81, v176, v144
	v_fmac_f32_e32 v81, v177, v145
	v_fmac_f32_e32 v81, v178, v146
	v_fmac_f32_e32 v81, v179, v147
	v_fma_f32 v82, v180, v132, 0
	v_fmac_f32_e32 v82, v181, v133
	v_fmac_f32_e32 v82, v182, v134
	v_fmac_f32_e32 v82, v183, v135
	v_fmac_f32_e32 v82, v184, v136
	v_fmac_f32_e32 v82, v185, v137
	v_fmac_f32_e32 v82, v186, v138
	v_fmac_f32_e32 v82, v187, v139
	v_fmac_f32_e32 v82, v188, v140
	v_fmac_f32_e32 v82, v189, v141
	v_fmac_f32_e32 v82, v190, v142
	v_fmac_f32_e32 v82, v191, v143
	v_fmac_f32_e32 v82, v192, v144
	v_fmac_f32_e32 v82, v193, v145
	v_fmac_f32_e32 v82, v194, v146
	v_fmac_f32_e32 v82, v195, v147
	v_fma_f32 v83, v196, v132, 0
	v_fmac_f32_e32 v83, v197, v133
	v_fmac_f32_e32 v83, v198, v134
	v_fmac_f32_e32 v83, v199, v135
	v_fmac_f32_e32 v83, v200, v136
	v_fmac_f32_e32 v83, v201, v137
	v_fmac_f32_e32 v83, v202, v138
	v_fmac_f32_e32 v83, v203, v139
	v_fmac_f32_e32 v83, v204, v140
	v_fmac_f32_e32 v83, v205, v141
	v_fmac_f32_e32 v83, v206, v142
	v_fmac_f32_e32 v83, v207, v143
	v_fmac_f32_e32 v83, v208, v144
	v_fmac_f32_e32 v83, v209, v145
	v_fmac_f32_e32 v83, v210, v146
	v_fmac_f32_e32 v83, v211, v147
	global_load_dwordx4 v[148:151], v8, s[24:25]
	global_load_dwordx4 v[152:155], v8, s[24:25] offset:16
	global_load_dwordx4 v[156:159], v8, s[24:25] offset:32
	global_load_dwordx4 v[160:163], v8, s[24:25] offset:48
	v_add_u32_e32 v8, s65, v8
	global_load_dwordx4 v[164:167], v8, s[24:25]
	global_load_dwordx4 v[168:171], v8, s[24:25] offset:16
	global_load_dwordx4 v[172:175], v8, s[24:25] offset:32
	global_load_dwordx4 v[176:179], v8, s[24:25] offset:48
	v_add_u32_e32 v8, s65, v8
	global_load_dwordx4 v[180:183], v8, s[24:25]
	global_load_dwordx4 v[184:187], v8, s[24:25] offset:16
	global_load_dwordx4 v[188:191], v8, s[24:25] offset:32
	global_load_dwordx4 v[192:195], v8, s[24:25] offset:48
	v_add_u32_e32 v8, s65, v8
	global_load_dwordx4 v[196:199], v8, s[24:25]
	global_load_dwordx4 v[200:203], v8, s[24:25] offset:16
	global_load_dwordx4 v[204:207], v8, s[24:25] offset:32
	global_load_dwordx4 v[208:211], v8, s[24:25] offset:48
	v_add_u32_e32 v8, s65, v8
	s_waitcnt vmcnt(0)
	v_fma_f32 v84, v148, v132, 0
	v_fmac_f32_e32 v84, v149, v133
	v_fmac_f32_e32 v84, v150, v134
	v_fmac_f32_e32 v84, v151, v135
	v_fmac_f32_e32 v84, v152, v136
	v_fmac_f32_e32 v84, v153, v137
	v_fmac_f32_e32 v84, v154, v138
	v_fmac_f32_e32 v84, v155, v139
	v_fmac_f32_e32 v84, v156, v140
	v_fmac_f32_e32 v84, v157, v141
	v_fmac_f32_e32 v84, v158, v142
	v_fmac_f32_e32 v84, v159, v143
	v_fmac_f32_e32 v84, v160, v144
	v_fmac_f32_e32 v84, v161, v145
	v_fmac_f32_e32 v84, v162, v146
	v_fmac_f32_e32 v84, v163, v147
	v_fma_f32 v85, v164, v132, 0
	v_fmac_f32_e32 v85, v165, v133
	v_fmac_f32_e32 v85, v166, v134
	v_fmac_f32_e32 v85, v167, v135
	v_fmac_f32_e32 v85, v168, v136
	v_fmac_f32_e32 v85, v169, v137
	v_fmac_f32_e32 v85, v170, v138
	v_fmac_f32_e32 v85, v171, v139
	v_fmac_f32_e32 v85, v172, v140
	v_fmac_f32_e32 v85, v173, v141
	v_fmac_f32_e32 v85, v174, v142
	v_fmac_f32_e32 v85, v175, v143
	v_fmac_f32_e32 v85, v176, v144
	v_fmac_f32_e32 v85, v177, v145
	v_fmac_f32_e32 v85, v178, v146
	v_fmac_f32_e32 v85, v179, v147
	v_fma_f32 v86, v180, v132, 0
	v_fmac_f32_e32 v86, v181, v133
	v_fmac_f32_e32 v86, v182, v134
	v_fmac_f32_e32 v86, v183, v135
	v_fmac_f32_e32 v86, v184, v136
	v_fmac_f32_e32 v86, v185, v137
	v_fmac_f32_e32 v86, v186, v138
	v_fmac_f32_e32 v86, v187, v139
	v_fmac_f32_e32 v86, v188, v140
	v_fmac_f32_e32 v86, v189, v141
	v_fmac_f32_e32 v86, v190, v142
	v_fmac_f32_e32 v86, v191, v143
	v_fmac_f32_e32 v86, v192, v144
	v_fmac_f32_e32 v86, v193, v145
	v_fmac_f32_e32 v86, v194, v146
	v_fmac_f32_e32 v86, v195, v147
	v_fma_f32 v87, v196, v132, 0
	v_fmac_f32_e32 v87, v197, v133
	v_fmac_f32_e32 v87, v198, v134
	v_fmac_f32_e32 v87, v199, v135
	v_fmac_f32_e32 v87, v200, v136
	v_fmac_f32_e32 v87, v201, v137
	v_fmac_f32_e32 v87, v202, v138
	v_fmac_f32_e32 v87, v203, v139
	v_fmac_f32_e32 v87, v204, v140
	v_fmac_f32_e32 v87, v205, v141
	v_fmac_f32_e32 v87, v206, v142
	v_fmac_f32_e32 v87, v207, v143
	v_fmac_f32_e32 v87, v208, v144
	v_fmac_f32_e32 v87, v209, v145
	v_fmac_f32_e32 v87, v210, v146
	v_fmac_f32_e32 v87, v211, v147
	s_bitset1_b32 s90, 1
	s_bitset1_b32 s90, 5
	s_add_i32 s4, s31, 2
	s_cmpk_gt_i32 s4, 0x1a7f
	s_cbranch_scc1 .LBB0_414
	s_branch .Lpro_c1
	v_mov_b64_e32 v[8:9], s[24:25]
	v_mad_i64_i32 v[8:9], s[28:29], v10, s65, v[8:9]
	v_lshl_add_u64 v[34:35], v[8:9], 0, s[10:11]
	v_add_co_u32_e32 v8, vcc, 0x3000, v8
	s_nop 1
	v_addc_co_u32_e32 v9, vcc, 0, v9, vcc
	global_load_dwordx4 v[22:25], v[8:9], off offset:2048
	global_load_dwordx4 v[26:29], v[34:35], off offset:48
	global_load_dwordx4 v[30:33], v[34:35], off offset:32
	s_nop 0
	global_load_dwordx4 v[34:37], v[34:35], off offset:16
	v_lshl_add_u64 v[8:9], s[26:27], 0, v[4:5]
	v_add_co_u32_e32 v38, vcc, s67, v8
	s_nop 1
	v_addc_co_u32_e32 v39, vcc, 0, v9, vcc
	v_add_co_u32_e32 v40, vcc, s84, v8
	s_nop 1
	v_addc_co_u32_e32 v41, vcc, 0, v9, vcc
	v_add_co_u32_e32 v8, vcc, s66, v8
	global_load_dword v43, v[38:39], off offset:1024
	global_load_dword v44, v[38:39], off offset:2048
	global_load_dword v45, v[38:39], off offset:3072
	global_load_dword v7, v4, s[26:27] offset:1024
	global_load_dword v42, v[40:41], off offset:-4096
	s_nop 0
	global_load_dword v38, v[40:41], off
	global_load_dword v39, v[40:41], off offset:1024
	global_load_dword v46, v[40:41], off offset:2048
	global_load_dword v47, v[40:41], off offset:3072
	v_addc_co_u32_e32 v9, vcc, 0, v9, vcc
	global_load_dword v50, v4, s[26:27]
	global_load_dword v40, v[8:9], off
	global_load_dword v41, v[8:9], off offset:1024
	global_load_dword v48, v[8:9], off offset:2048
	global_load_dword v49, v[8:9], off offset:3072
	global_load_dword v51, v4, s[26:27] offset:2048
	global_load_dword v52, v4, s[26:27] offset:3072
	s_waitcnt vmcnt(11)
	v_pk_mul_f32 v[8:9], v[34:35], v[42:43]
	v_pk_mul_f32 v[34:35], v[36:37], v[44:45]
	s_waitcnt vmcnt(6)
	v_fma_f32 v36, v22, v50, 0
	v_fmac_f32_e32 v36, v23, v7
	v_pk_mul_f32 v[30:31], v[30:31], v[38:39]
	v_pk_mul_f32 v[32:33], v[32:33], v[46:47]
	s_waitcnt vmcnt(1)
	v_fmac_f32_e32 v36, v24, v51
	s_waitcnt vmcnt(0)
	v_fmac_f32_e32 v36, v25, v52
	v_add_f32_e32 v7, v36, v8
	v_add_f32_e32 v7, v7, v9
	v_add_f32_e32 v7, v7, v34
	v_add_f32_e32 v7, v7, v35
	v_add_f32_e32 v7, v7, v30
	v_add_f32_e32 v7, v7, v31
	v_add_f32_e32 v7, v7, v32
	v_pk_mul_f32 v[22:23], v[26:27], v[40:41]
	v_add_f32_e32 v7, v7, v33
	v_add_f32_e32 v7, v7, v22
	v_pk_mul_f32 v[26:27], v[28:29], v[48:49]
	v_add_f32_e32 v7, v7, v23
	v_add_f32_e32 v7, v7, v26
	v_add_f32_e32 v7, v7, v27
	v_lshl_add_u64 v[8:9], s[6:7], 0, v[4:5]
	s_cbranch_execnz .LBB0_174

.LBB0_272:
	s_cmp_lg_u64 s[26:27], 0
	s_cselect_b64 s[4:5], -1, 0
	s_ashr_i32 s7, s6, 31
	s_lshl_b64 s[6:7], s[6:7], 2
	s_add_u32 s6, s24, s6
	s_addc_u32 s7, s25, s7
	v_add_u32_e32 v10, s22, v2
	s_cmp_eq_u64 s[26:27], 0
	v_ashrrev_i32_e32 v11, 31, v10
	s_cbranch_scc1 .LBB0_481
	v_mov_b32_e32 v8, v4
	global_load_dword v132, v8, s[26:27]
	global_load_dword v133, v8, s[26:27] offset:1024
	global_load_dword v134, v8, s[26:27] offset:2048
	global_load_dword v135, v8, s[26:27] offset:3072
	v_add_u32_e32 v8, 0x1000, v8
	global_load_dword v136, v8, s[26:27]
	global_load_dword v137, v8, s[26:27] offset:1024
	global_load_dword v138, v8, s[26:27] offset:2048
	global_load_dword v139, v8, s[26:27] offset:3072
	v_add_u32_e32 v8, 0x1000, v8
	global_load_dword v140, v8, s[26:27]
	global_load_dword v141, v8, s[26:27] offset:1024
	global_load_dword v142, v8, s[26:27] offset:2048
	global_load_dword v143, v8, s[26:27] offset:3072
	v_add_u32_e32 v8, 0x1000, v8
	global_load_dword v144, v8, s[26:27]
	global_load_dword v145, v8, s[26:27] offset:1024
	global_load_dword v146, v8, s[26:27] offset:2048
	global_load_dword v147, v8, s[26:27] offset:3072
	v_lshlrev_b32_e32 v9, 2, v10
	global_load_dwordx4 v[104:107], v9, s[18:19]
	global_load_dwordx4 v[108:111], v9, s[18:19] offset:16
	v_mul_lo_u32 v8, v10, s65
	v_add_u32_e32 v8, 0x3800, v8
	global_load_dwordx4 v[148:151], v8, s[24:25]
	global_load_dwordx4 v[152:155], v8, s[24:25] offset:16
	global_load_dwordx4 v[156:159], v8, s[24:25] offset:32
	global_load_dwordx4 v[160:163], v8, s[24:25] offset:48
	v_add_u32_e32 v8, s65, v8
	global_load_dwordx4 v[164:167], v8, s[24:25]
	global_load_dwordx4 v[168:171], v8, s[24:25] offset:16
	global_load_dwordx4 v[172:175], v8, s[24:25] offset:32
	global_load_dwordx4 v[176:179], v8, s[24:25] offset:48
	v_add_u32_e32 v8, s65, v8
	global_load_dwordx4 v[180:183], v8, s[24:25]
	global_load_dwordx4 v[184:187], v8, s[24:25] offset:16
	global_load_dwordx4 v[188:191], v8, s[24:25] offset:32
	global_load_dwordx4 v[192:195], v8, s[24:25] offset:48
	v_add_u32_e32 v8, s65, v8
	global_load_dwordx4 v[196:199], v8, s[24:25]
	global_load_dwordx4 v[200:203], v8, s[24:25] offset:16
	global_load_dwordx4 v[204:207], v8, s[24:25] offset:32
	global_load_dwordx4 v[208:211], v8, s[24:25] offset:48
	v_add_u32_e32 v8, s65, v8
	s_waitcnt vmcnt(0)
	v_fma_f32 v96, v148, v132, 0
	v_fmac_f32_e32 v96, v149, v133
	v_fmac_f32_e32 v96, v150, v134
	v_fmac_f32_e32 v96, v151, v135
	v_fmac_f32_e32 v96, v152, v136
	v_fmac_f32_e32 v96, v153, v137
	v_fmac_f32_e32 v96, v154, v138
	v_fmac_f32_e32 v96, v155, v139
	v_fmac_f32_e32 v96, v156, v140
	v_fmac_f32_e32 v96, v157, v141
	v_fmac_f32_e32 v96, v158, v142
	v_fmac_f32_e32 v96, v159, v143
	v_fmac_f32_e32 v96, v160, v144
	v_fmac_f32_e32 v96, v161, v145
	v_fmac_f32_e32 v96, v162, v146
	v_fmac_f32_e32 v96, v163, v147
	v_fma_f32 v97, v164, v132, 0
	v_fmac_f32_e32 v97, v165, v133
	v_fmac_f32_e32 v97, v166, v134
	v_fmac_f32_e32 v97, v167, v135
	v_fmac_f32_e32 v97, v168, v136
	v_fmac_f32_e32 v97, v169, v137
	v_fmac_f32_e32 v97, v170, v138
	v_fmac_f32_e32 v97, v171, v139
	v_fmac_f32_e32 v97, v172, v140
	v_fmac_f32_e32 v97, v173, v141
	v_fmac_f32_e32 v97, v174, v142
	v_fmac_f32_e32 v97, v175, v143
	v_fmac_f32_e32 v97, v176, v144
	v_fmac_f32_e32 v97, v177, v145
	v_fmac_f32_e32 v97, v178, v146
	v_fmac_f32_e32 v97, v179, v147
	v_fma_f32 v98, v180, v132, 0
	v_fmac_f32_e32 v98, v181, v133
	v_fmac_f32_e32 v98, v182, v134
	v_fmac_f32_e32 v98, v183, v135
	v_fmac_f32_e32 v98, v184, v136
	v_fmac_f32_e32 v98, v185, v137
	v_fmac_f32_e32 v98, v186, v138
	v_fmac_f32_e32 v98, v187, v139
	v_fmac_f32_e32 v98, v188, v140
	v_fmac_f32_e32 v98, v189, v141
	v_fmac_f32_e32 v98, v190, v142
	v_fmac_f32_e32 v98, v191, v143
	v_fmac_f32_e32 v98, v192, v144
	v_fmac_f32_e32 v98, v193, v145
	v_fmac_f32_e32 v98, v194, v146
	v_fmac_f32_e32 v98, v195, v147
	v_fma_f32 v99, v196, v132, 0
	v_fmac_f32_e32 v99, v197, v133
	v_fmac_f32_e32 v99, v198, v134
	v_fmac_f32_e32 v99, v199, v135
	v_fmac_f32_e32 v99, v200, v136
	v_fmac_f32_e32 v99, v201, v137
	v_fmac_f32_e32 v99, v202, v138
	v_fmac_f32_e32 v99, v203, v139
	v_fmac_f32_e32 v99, v204, v140
	v_fmac_f32_e32 v99, v205, v141
	v_fmac_f32_e32 v99, v206, v142
	v_fmac_f32_e32 v99, v207, v143
	v_fmac_f32_e32 v99, v208, v144
	v_fmac_f32_e32 v99, v209, v145
	v_fmac_f32_e32 v99, v210, v146
	v_fmac_f32_e32 v99, v211, v147
	global_load_dwordx4 v[148:151], v8, s[24:25]
	global_load_dwordx4 v[152:155], v8, s[24:25] offset:16
	global_load_dwordx4 v[156:159], v8, s[24:25] offset:32
	global_load_dwordx4 v[160:163], v8, s[24:25] offset:48
	v_add_u32_e32 v8, s65, v8
	global_load_dwordx4 v[164:167], v8, s[24:25]
	global_load_dwordx4 v[168:171], v8, s[24:25] offset:16
	global_load_dwordx4 v[172:175], v8, s[24:25] offset:32
	global_load_dwordx4 v[176:179], v8, s[24:25] offset:48
	v_add_u32_e32 v8, s65, v8
	global_load_dwordx4 v[180:183], v8, s[24:25]
	global_load_dwordx4 v[184:187], v8, s[24:25] offset:16
	global_load_dwordx4 v[188:191], v8, s[24:25] offset:32
	global_load_dwordx4 v[192:195], v8, s[24:25] offset:48
	v_add_u32_e32 v8, s65, v8
	global_load_dwordx4 v[196:199], v8, s[24:25]
	global_load_dwordx4 v[200:203], v8, s[24:25] offset:16
	global_load_dwordx4 v[204:207], v8, s[24:25] offset:32
	global_load_dwordx4 v[208:211], v8, s[24:25] offset:48
	v_add_u32_e32 v8, s65, v8
	s_waitcnt vmcnt(0)
	v_fma_f32 v100, v148, v132, 0
	v_fmac_f32_e32 v100, v149, v133
	v_fmac_f32_e32 v100, v150, v134
	v_fmac_f32_e32 v100, v151, v135
	v_fmac_f32_e32 v100, v152, v136
	v_fmac_f32_e32 v100, v153, v137
	v_fmac_f32_e32 v100, v154, v138
	v_fmac_f32_e32 v100, v155, v139
	v_fmac_f32_e32 v100, v156, v140
	v_fmac_f32_e32 v100, v157, v141
	v_fmac_f32_e32 v100, v158, v142
	v_fmac_f32_e32 v100, v159, v143
	v_fmac_f32_e32 v100, v160, v144
	v_fmac_f32_e32 v100, v161, v145
	v_fmac_f32_e32 v100, v162, v146
	v_fmac_f32_e32 v100, v163, v147
	v_fma_f32 v101, v164, v132, 0
	v_fmac_f32_e32 v101, v165, v133
	v_fmac_f32_e32 v101, v166, v134
	v_fmac_f32_e32 v101, v167, v135
	v_fmac_f32_e32 v101, v168, v136
	v_fmac_f32_e32 v101, v169, v137
	v_fmac_f32_e32 v101, v170, v138
	v_fmac_f32_e32 v101, v171, v139
	v_fmac_f32_e32 v101, v172, v140
	v_fmac_f32_e32 v101, v173, v141
	v_fmac_f32_e32 v101, v174, v142
	v_fmac_f32_e32 v101, v175, v143
	v_fmac_f32_e32 v101, v176, v144
	v_fmac_f32_e32 v101, v177, v145
	v_fmac_f32_e32 v101, v178, v146
	v_fmac_f32_e32 v101, v179, v147
	v_fma_f32 v102, v180, v132, 0
	v_fmac_f32_e32 v102, v181, v133
	v_fmac_f32_e32 v102, v182, v134
	v_fmac_f32_e32 v102, v183, v135
	v_fmac_f32_e32 v102, v184, v136
	v_fmac_f32_e32 v102, v185, v137
	v_fmac_f32_e32 v102, v186, v138
	v_fmac_f32_e32 v102, v187, v139
	v_fmac_f32_e32 v102, v188, v140
	v_fmac_f32_e32 v102, v189, v141
	v_fmac_f32_e32 v102, v190, v142
	v_fmac_f32_e32 v102, v191, v143
	v_fmac_f32_e32 v102, v192, v144
	v_fmac_f32_e32 v102, v193, v145
	v_fmac_f32_e32 v102, v194, v146
	v_fmac_f32_e32 v102, v195, v147
	v_fma_f32 v103, v196, v132, 0
	v_fmac_f32_e32 v103, v197, v133
	v_fmac_f32_e32 v103, v198, v134
	v_fmac_f32_e32 v103, v199, v135
	v_fmac_f32_e32 v103, v200, v136
	v_fmac_f32_e32 v103, v201, v137
	v_fmac_f32_e32 v103, v202, v138
	v_fmac_f32_e32 v103, v203, v139
	v_fmac_f32_e32 v103, v204, v140
	v_fmac_f32_e32 v103, v205, v141
	v_fmac_f32_e32 v103, v206, v142
	v_fmac_f32_e32 v103, v207, v143
	v_fmac_f32_e32 v103, v208, v144
	v_fmac_f32_e32 v103, v209, v145
	v_fmac_f32_e32 v103, v210, v146
	v_fmac_f32_e32 v103, v211, v147
	s_bitset1_b32 s90, 2
	s_bitset1_b32 s90, 6
	s_add_i32 s4, s31, 3
	s_cmpk_gt_i32 s4, 0x1a7f
	s_cbranch_scc1 .LBB0_414
	s_branch .Lpro_c2
	v_mov_b64_e32 v[8:9], s[24:25]
	v_mad_i64_i32 v[8:9], s[28:29], v10, s65, v[8:9]
	v_lshl_add_u64 v[34:35], v[8:9], 0, s[10:11]
	v_add_co_u32_e32 v8, vcc, 0x3000, v8
	s_nop 1
	v_addc_co_u32_e32 v9, vcc, 0, v9, vcc
	global_load_dwordx4 v[22:25], v[8:9], off offset:2048
	global_load_dwordx4 v[26:29], v[34:35], off offset:48
	global_load_dwordx4 v[30:33], v[34:35], off offset:32
	s_nop 0
	global_load_dwordx4 v[34:37], v[34:35], off offset:16
	v_lshl_add_u64 v[8:9], s[26:27], 0, v[4:5]
	v_add_co_u32_e32 v38, vcc, s67, v8
	s_nop 1
	v_addc_co_u32_e32 v39, vcc, 0, v9, vcc
	v_add_co_u32_e32 v40, vcc, s84, v8
	s_nop 1
	v_addc_co_u32_e32 v41, vcc, 0, v9, vcc
	v_add_co_u32_e32 v8, vcc, s66, v8
	global_load_dword v43, v[38:39], off offset:1024
	global_load_dword v44, v[38:39], off offset:2048
	global_load_dword v45, v[38:39], off offset:3072
	global_load_dword v7, v4, s[26:27] offset:1024
	global_load_dword v42, v[40:41], off offset:-4096
	s_nop 0
	global_load_dword v38, v[40:41], off
	global_load_dword v39, v[40:41], off offset:1024
	global_load_dword v46, v[40:41], off offset:2048
	global_load_dword v47, v[40:41], off offset:3072
	v_addc_co_u32_e32 v9, vcc, 0, v9, vcc
	global_load_dword v50, v4, s[26:27]
	global_load_dword v40, v[8:9], off
	global_load_dword v41, v[8:9], off offset:1024
	global_load_dword v48, v[8:9], off offset:2048
	global_load_dword v49, v[8:9], off offset:3072
	global_load_dword v51, v4, s[26:27] offset:2048
	global_load_dword v52, v4, s[26:27] offset:3072
	s_waitcnt vmcnt(11)
	v_pk_mul_f32 v[8:9], v[34:35], v[42:43]
	v_pk_mul_f32 v[34:35], v[36:37], v[44:45]
	s_waitcnt vmcnt(6)
	v_fma_f32 v36, v22, v50, 0
	v_fmac_f32_e32 v36, v23, v7
	v_pk_mul_f32 v[30:31], v[30:31], v[38:39]
	v_pk_mul_f32 v[32:33], v[32:33], v[46:47]
	s_waitcnt vmcnt(1)
	v_fmac_f32_e32 v36, v24, v51
	s_waitcnt vmcnt(0)
	v_fmac_f32_e32 v36, v25, v52
	v_add_f32_e32 v7, v36, v8
	v_add_f32_e32 v7, v7, v9
	v_add_f32_e32 v7, v7, v34
	v_add_f32_e32 v7, v7, v35
	v_add_f32_e32 v7, v7, v30
	v_add_f32_e32 v7, v7, v31
	v_add_f32_e32 v7, v7, v32
	v_pk_mul_f32 v[22:23], v[26:27], v[40:41]
	v_add_f32_e32 v7, v7, v33
	v_add_f32_e32 v7, v7, v22
	v_pk_mul_f32 v[26:27], v[28:29], v[48:49]
	v_add_f32_e32 v7, v7, v23
	v_add_f32_e32 v7, v7, v26
	v_add_f32_e32 v7, v7, v27
	v_lshl_add_u64 v[8:9], s[6:7], 0, v[4:5]
	s_cbranch_execnz .LBB0_275

.LBB0_373:
	s_cmp_lg_u64 s[26:27], 0
	s_cselect_b64 s[4:5], -1, 0
	s_ashr_i32 s7, s6, 31
	s_lshl_b64 s[6:7], s[6:7], 2
	s_add_u32 s6, s24, s6
	s_addc_u32 s7, s25, s7
	v_add_u32_e32 v10, s22, v2
	s_cmp_eq_u64 s[26:27], 0
	v_ashrrev_i32_e32 v11, 31, v10
	s_cbranch_scc1 .LBB0_489
	v_mov_b32_e32 v8, v4
	global_load_dword v132, v8, s[26:27]
	global_load_dword v133, v8, s[26:27] offset:1024
	global_load_dword v134, v8, s[26:27] offset:2048
	global_load_dword v135, v8, s[26:27] offset:3072
	v_add_u32_e32 v8, 0x1000, v8
	global_load_dword v136, v8, s[26:27]
	global_load_dword v137, v8, s[26:27] offset:1024
	global_load_dword v138, v8, s[26:27] offset:2048
	global_load_dword v139, v8, s[26:27] offset:3072
	v_add_u32_e32 v8, 0x1000, v8
	global_load_dword v140, v8, s[26:27]
	global_load_dword v141, v8, s[26:27] offset:1024
	global_load_dword v142, v8, s[26:27] offset:2048
	global_load_dword v143, v8, s[26:27] offset:3072
	v_add_u32_e32 v8, 0x1000, v8
	global_load_dword v144, v8, s[26:27]
	global_load_dword v145, v8, s[26:27] offset:1024
	global_load_dword v146, v8, s[26:27] offset:2048
	global_load_dword v147, v8, s[26:27] offset:3072
	v_lshlrev_b32_e32 v9, 2, v10
	global_load_dwordx4 v[120:123], v9, s[18:19]
	global_load_dwordx4 v[124:127], v9, s[18:19] offset:16
	v_mul_lo_u32 v8, v10, s65
	v_add_u32_e32 v8, 0x3800, v8
	global_load_dwordx4 v[148:151], v8, s[24:25]
	global_load_dwordx4 v[152:155], v8, s[24:25] offset:16
	global_load_dwordx4 v[156:159], v8, s[24:25] offset:32
	global_load_dwordx4 v[160:163], v8, s[24:25] offset:48
	v_add_u32_e32 v8, s65, v8
	global_load_dwordx4 v[164:167], v8, s[24:25]
	global_load_dwordx4 v[168:171], v8, s[24:25] offset:16
	global_load_dwordx4 v[172:175], v8, s[24:25] offset:32
	global_load_dwordx4 v[176:179], v8, s[24:25] offset:48
	v_add_u32_e32 v8, s65, v8
	global_load_dwordx4 v[180:183], v8, s[24:25]
	global_load_dwordx4 v[184:187], v8, s[24:25] offset:16
	global_load_dwordx4 v[188:191], v8, s[24:25] offset:32
	global_load_dwordx4 v[192:195], v8, s[24:25] offset:48
	v_add_u32_e32 v8, s65, v8
	global_load_dwordx4 v[196:199], v8, s[24:25]
	global_load_dwordx4 v[200:203], v8, s[24:25] offset:16
	global_load_dwordx4 v[204:207], v8, s[24:25] offset:32
	global_load_dwordx4 v[208:211], v8, s[24:25] offset:48
	v_add_u32_e32 v8, s65, v8
	s_waitcnt vmcnt(0)
	v_fma_f32 v112, v148, v132, 0
	v_fmac_f32_e32 v112, v149, v133
	v_fmac_f32_e32 v112, v150, v134
	v_fmac_f32_e32 v112, v151, v135
	v_fmac_f32_e32 v112, v152, v136
	v_fmac_f32_e32 v112, v153, v137
	v_fmac_f32_e32 v112, v154, v138
	v_fmac_f32_e32 v112, v155, v139
	v_fmac_f32_e32 v112, v156, v140
	v_fmac_f32_e32 v112, v157, v141
	v_fmac_f32_e32 v112, v158, v142
	v_fmac_f32_e32 v112, v159, v143
	v_fmac_f32_e32 v112, v160, v144
	v_fmac_f32_e32 v112, v161, v145
	v_fmac_f32_e32 v112, v162, v146
	v_fmac_f32_e32 v112, v163, v147
	v_fma_f32 v113, v164, v132, 0
	v_fmac_f32_e32 v113, v165, v133
	v_fmac_f32_e32 v113, v166, v134
	v_fmac_f32_e32 v113, v167, v135
	v_fmac_f32_e32 v113, v168, v136
	v_fmac_f32_e32 v113, v169, v137
	v_fmac_f32_e32 v113, v170, v138
	v_fmac_f32_e32 v113, v171, v139
	v_fmac_f32_e32 v113, v172, v140
	v_fmac_f32_e32 v113, v173, v141
	v_fmac_f32_e32 v113, v174, v142
	v_fmac_f32_e32 v113, v175, v143
	v_fmac_f32_e32 v113, v176, v144
	v_fmac_f32_e32 v113, v177, v145
	v_fmac_f32_e32 v113, v178, v146
	v_fmac_f32_e32 v113, v179, v147
	v_fma_f32 v114, v180, v132, 0
	v_fmac_f32_e32 v114, v181, v133
	v_fmac_f32_e32 v114, v182, v134
	v_fmac_f32_e32 v114, v183, v135
	v_fmac_f32_e32 v114, v184, v136
	v_fmac_f32_e32 v114, v185, v137
	v_fmac_f32_e32 v114, v186, v138
	v_fmac_f32_e32 v114, v187, v139
	v_fmac_f32_e32 v114, v188, v140
	v_fmac_f32_e32 v114, v189, v141
	v_fmac_f32_e32 v114, v190, v142
	v_fmac_f32_e32 v114, v191, v143
	v_fmac_f32_e32 v114, v192, v144
	v_fmac_f32_e32 v114, v193, v145
	v_fmac_f32_e32 v114, v194, v146
	v_fmac_f32_e32 v114, v195, v147
	v_fma_f32 v115, v196, v132, 0
	v_fmac_f32_e32 v115, v197, v133
	v_fmac_f32_e32 v115, v198, v134
	v_fmac_f32_e32 v115, v199, v135
	v_fmac_f32_e32 v115, v200, v136
	v_fmac_f32_e32 v115, v201, v137
	v_fmac_f32_e32 v115, v202, v138
	v_fmac_f32_e32 v115, v203, v139
	v_fmac_f32_e32 v115, v204, v140
	v_fmac_f32_e32 v115, v205, v141
	v_fmac_f32_e32 v115, v206, v142
	v_fmac_f32_e32 v115, v207, v143
	v_fmac_f32_e32 v115, v208, v144
	v_fmac_f32_e32 v115, v209, v145
	v_fmac_f32_e32 v115, v210, v146
	v_fmac_f32_e32 v115, v211, v147
	global_load_dwordx4 v[148:151], v8, s[24:25]
	global_load_dwordx4 v[152:155], v8, s[24:25] offset:16
	global_load_dwordx4 v[156:159], v8, s[24:25] offset:32
	global_load_dwordx4 v[160:163], v8, s[24:25] offset:48
	v_add_u32_e32 v8, s65, v8
	global_load_dwordx4 v[164:167], v8, s[24:25]
	global_load_dwordx4 v[168:171], v8, s[24:25] offset:16
	global_load_dwordx4 v[172:175], v8, s[24:25] offset:32
	global_load_dwordx4 v[176:179], v8, s[24:25] offset:48
	v_add_u32_e32 v8, s65, v8
	global_load_dwordx4 v[180:183], v8, s[24:25]
	global_load_dwordx4 v[184:187], v8, s[24:25] offset:16
	global_load_dwordx4 v[188:191], v8, s[24:25] offset:32
	global_load_dwordx4 v[192:195], v8, s[24:25] offset:48
	v_add_u32_e32 v8, s65, v8
	global_load_dwordx4 v[196:199], v8, s[24:25]
	global_load_dwordx4 v[200:203], v8, s[24:25] offset:16
	global_load_dwordx4 v[204:207], v8, s[24:25] offset:32
	global_load_dwordx4 v[208:211], v8, s[24:25] offset:48
	v_add_u32_e32 v8, s65, v8
	s_waitcnt vmcnt(0)
	v_fma_f32 v116, v148, v132, 0
	v_fmac_f32_e32 v116, v149, v133
	v_fmac_f32_e32 v116, v150, v134
	v_fmac_f32_e32 v116, v151, v135
	v_fmac_f32_e32 v116, v152, v136
	v_fmac_f32_e32 v116, v153, v137
	v_fmac_f32_e32 v116, v154, v138
	v_fmac_f32_e32 v116, v155, v139
	v_fmac_f32_e32 v116, v156, v140
	v_fmac_f32_e32 v116, v157, v141
	v_fmac_f32_e32 v116, v158, v142
	v_fmac_f32_e32 v116, v159, v143
	v_fmac_f32_e32 v116, v160, v144
	v_fmac_f32_e32 v116, v161, v145
	v_fmac_f32_e32 v116, v162, v146
	v_fmac_f32_e32 v116, v163, v147
	v_fma_f32 v117, v164, v132, 0
	v_fmac_f32_e32 v117, v165, v133
	v_fmac_f32_e32 v117, v166, v134
	v_fmac_f32_e32 v117, v167, v135
	v_fmac_f32_e32 v117, v168, v136
	v_fmac_f32_e32 v117, v169, v137
	v_fmac_f32_e32 v117, v170, v138
	v_fmac_f32_e32 v117, v171, v139
	v_fmac_f32_e32 v117, v172, v140
	v_fmac_f32_e32 v117, v173, v141
	v_fmac_f32_e32 v117, v174, v142
	v_fmac_f32_e32 v117, v175, v143
	v_fmac_f32_e32 v117, v176, v144
	v_fmac_f32_e32 v117, v177, v145
	v_fmac_f32_e32 v117, v178, v146
	v_fmac_f32_e32 v117, v179, v147
	v_fma_f32 v118, v180, v132, 0
	v_fmac_f32_e32 v118, v181, v133
	v_fmac_f32_e32 v118, v182, v134
	v_fmac_f32_e32 v118, v183, v135
	v_fmac_f32_e32 v118, v184, v136
	v_fmac_f32_e32 v118, v185, v137
	v_fmac_f32_e32 v118, v186, v138
	v_fmac_f32_e32 v118, v187, v139
	v_fmac_f32_e32 v118, v188, v140
	v_fmac_f32_e32 v118, v189, v141
	v_fmac_f32_e32 v118, v190, v142
	v_fmac_f32_e32 v118, v191, v143
	v_fmac_f32_e32 v118, v192, v144
	v_fmac_f32_e32 v118, v193, v145
	v_fmac_f32_e32 v118, v194, v146
	v_fmac_f32_e32 v118, v195, v147
	v_fma_f32 v119, v196, v132, 0
	v_fmac_f32_e32 v119, v197, v133
	v_fmac_f32_e32 v119, v198, v134
	v_fmac_f32_e32 v119, v199, v135
	v_fmac_f32_e32 v119, v200, v136
	v_fmac_f32_e32 v119, v201, v137
	v_fmac_f32_e32 v119, v202, v138
	v_fmac_f32_e32 v119, v203, v139
	v_fmac_f32_e32 v119, v204, v140
	v_fmac_f32_e32 v119, v205, v141
	v_fmac_f32_e32 v119, v206, v142
	v_fmac_f32_e32 v119, v207, v143
	v_fmac_f32_e32 v119, v208, v144
	v_fmac_f32_e32 v119, v209, v145
	v_fmac_f32_e32 v119, v210, v146
	v_fmac_f32_e32 v119, v211, v147
	s_bitset1_b32 s90, 3
	s_bitset1_b32 s90, 7
	s_branch .LBB0_414
	v_mov_b64_e32 v[8:9], s[24:25]
	v_mad_i64_i32 v[8:9], s[28:29], v10, s65, v[8:9]
	v_lshl_add_u64 v[34:35], v[8:9], 0, s[10:11]
	v_add_co_u32_e32 v8, vcc, 0x3000, v8
	s_nop 1
	v_addc_co_u32_e32 v9, vcc, 0, v9, vcc
	global_load_dwordx4 v[22:25], v[8:9], off offset:2048
	global_load_dwordx4 v[26:29], v[34:35], off offset:48
	global_load_dwordx4 v[30:33], v[34:35], off offset:32
	s_nop 0
	global_load_dwordx4 v[34:37], v[34:35], off offset:16
	v_lshl_add_u64 v[8:9], s[26:27], 0, v[4:5]
	v_add_co_u32_e32 v38, vcc, s67, v8
	s_nop 1
	v_addc_co_u32_e32 v39, vcc, 0, v9, vcc
	v_add_co_u32_e32 v40, vcc, s84, v8
	s_nop 1
	v_addc_co_u32_e32 v41, vcc, 0, v9, vcc
	v_add_co_u32_e32 v8, vcc, s66, v8
	global_load_dword v43, v[38:39], off offset:1024
	global_load_dword v44, v[38:39], off offset:2048
	global_load_dword v45, v[38:39], off offset:3072
	global_load_dword v7, v4, s[26:27] offset:1024
	global_load_dword v42, v[40:41], off offset:-4096
	s_nop 0
	global_load_dword v38, v[40:41], off
	global_load_dword v39, v[40:41], off offset:1024
	global_load_dword v46, v[40:41], off offset:2048
	global_load_dword v47, v[40:41], off offset:3072
	v_addc_co_u32_e32 v9, vcc, 0, v9, vcc
	global_load_dword v50, v4, s[26:27]
	global_load_dword v40, v[8:9], off
	global_load_dword v41, v[8:9], off offset:1024
	global_load_dword v48, v[8:9], off offset:2048
	global_load_dword v49, v[8:9], off offset:3072
	global_load_dword v51, v4, s[26:27] offset:2048
	global_load_dword v52, v4, s[26:27] offset:3072
	s_waitcnt vmcnt(11)
	v_pk_mul_f32 v[8:9], v[34:35], v[42:43]
	v_pk_mul_f32 v[34:35], v[36:37], v[44:45]
	s_waitcnt vmcnt(6)
	v_fma_f32 v36, v22, v50, 0
	v_fmac_f32_e32 v36, v23, v7
	v_pk_mul_f32 v[30:31], v[30:31], v[38:39]
	v_pk_mul_f32 v[32:33], v[32:33], v[46:47]
	s_waitcnt vmcnt(1)
	v_fmac_f32_e32 v36, v24, v51
	s_waitcnt vmcnt(0)
	v_fmac_f32_e32 v36, v25, v52
	v_add_f32_e32 v7, v36, v8
	v_add_f32_e32 v7, v7, v9
	v_add_f32_e32 v7, v7, v34
	v_add_f32_e32 v7, v7, v35
	v_add_f32_e32 v7, v7, v30
	v_add_f32_e32 v7, v7, v31
	v_add_f32_e32 v7, v7, v32
	v_pk_mul_f32 v[22:23], v[26:27], v[40:41]
	v_add_f32_e32 v7, v7, v33
	v_add_f32_e32 v7, v7, v22
	v_pk_mul_f32 v[26:27], v[28:29], v[48:49]
	v_add_f32_e32 v7, v7, v23
	v_add_f32_e32 v7, v7, v26
	v_add_f32_e32 v7, v7, v27
	v_lshl_add_u64 v[8:9], s[6:7], 0, v[4:5]
	s_cbranch_execnz .LBB0_376

.LBB0_1093:
	s_cmpk_lt_i32 s10, 0x900
	s_mov_b64 s[0:1], -1
	s_cbranch_scc0 .LBB0_1103
	s_cmpk_gt_i32 s10, 0x3ff
	s_cbranch_scc0 .LBB0_1100
	s_cmpk_gt_u32 s10, 0x7ff
	s_cbranch_scc0 .LBB0_1097
	s_add_i32 s0, s10, 0xfffff800
	s_and_b32 s96, s0, 0xffffffc0
	s_and_b32 s2, s10, 63
	s_lshl_b64 s[0:1], s[96:97], 11
	v_readlane_b32 s11, v252, 46
	s_add_u32 s11, s11, s0
	v_readlane_b32 s0, v252, 47
	s_waitcnt vmcnt(4)
	v_mov_b32_e32 v4, v232
	s_addc_u32 s12, s0, s1
	s_add_i32 s0, s8, 0xfffe0000
	s_waitcnt vmcnt(0)
	v_ashrrev_i32_e32 v0, 3, v4
	s_and_b32 s0, s0, 0x7ffff000
	s_lshl_b32 s1, s2, 6
	v_and_b32_e32 v0, -8, v0
	s_or_b32 s96, s1, s0
	v_ashrrev_i32_e32 v1, 31, v0
	v_lshl_add_u64 v[0:1], s[96:97], 0, v[0:1]
	v_mov_b64_e32 v[2:3], s[82:83]
	s_movk_i32 s13, 0x3800
	v_mad_u64_u32 v[8:9], s[0:1], v0, s13, v[2:3]
	v_lshlrev_b32_e32 v0, 3, v4
	v_and_b32_e32 v10, 0x1f8, v0
	v_mad_i32_i24 v9, v1, s13, v9
	v_lshlrev_b32_e32 v16, 1, v10
	s_lshl_b32 s0, s2, 11
	v_lshl_add_u64 v[12:13], v[8:9], 0, v[16:17]
	s_add_u32 s0, s11, s0
	v_add_co_u32_e32 v14, vcc, s57, v12
	s_addc_u32 s1, s12, 0
	v_lshlrev_b32_e32 v4, 2, v10
	v_addc_co_u32_e32 v15, vcc, 0, v13, vcc
	global_load_dwordx4 v[0:3], v4, s[0:1] offset:16
	s_nop 0
	global_load_dwordx4 v[4:7], v4, s[0:1]
	s_mov_b64 s[0:1], 0x3800
	v_mov_b64_e32 v[24:25], v[12:13]
	v_add_co_u32_e32 v14, vcc, 0x3000, v12
	s_nop 1
	v_addc_co_u32_e32 v15, vcc, 0, v13, vcc
	global_load_dwordx4 v[32:35], v[12:13], off offset:3072
	global_load_dwordx4 v[64:67], v[14:15], off offset:1024
	v_lshl_add_u64 v[12:13], v[12:13], 0, s[0:1]
	v_lshl_add_u64 v[14:15], v[14:15], 0, s[0:1]
	global_load_dwordx4 v[36:39], v[12:13], off offset:3072
	global_load_dwordx4 v[68:71], v[14:15], off offset:1024
	v_lshl_add_u64 v[12:13], v[12:13], 0, s[0:1]
	v_lshl_add_u64 v[14:15], v[14:15], 0, s[0:1]
	global_load_dwordx4 v[40:43], v[12:13], off offset:3072
	global_load_dwordx4 v[72:75], v[14:15], off offset:1024
	v_lshl_add_u64 v[12:13], v[12:13], 0, s[0:1]
	v_lshl_add_u64 v[14:15], v[14:15], 0, s[0:1]
	global_load_dwordx4 v[44:47], v[12:13], off offset:3072
	global_load_dwordx4 v[76:79], v[14:15], off offset:1024
	v_lshl_add_u64 v[12:13], v[12:13], 0, s[0:1]
	v_lshl_add_u64 v[14:15], v[14:15], 0, s[0:1]
	global_load_dwordx4 v[48:51], v[12:13], off offset:3072
	global_load_dwordx4 v[80:83], v[14:15], off offset:1024
	v_lshl_add_u64 v[12:13], v[12:13], 0, s[0:1]
	v_lshl_add_u64 v[14:15], v[14:15], 0, s[0:1]
	global_load_dwordx4 v[52:55], v[12:13], off offset:3072
	global_load_dwordx4 v[84:87], v[14:15], off offset:1024
	v_lshl_add_u64 v[12:13], v[12:13], 0, s[0:1]
	v_lshl_add_u64 v[14:15], v[14:15], 0, s[0:1]
	global_load_dwordx4 v[56:59], v[12:13], off offset:3072
	global_load_dwordx4 v[88:91], v[14:15], off offset:1024
	v_lshl_add_u64 v[12:13], v[12:13], 0, s[0:1]
	v_lshl_add_u64 v[14:15], v[14:15], 0, s[0:1]
	global_load_dwordx4 v[60:63], v[12:13], off offset:3072
	global_load_dwordx4 v[92:95], v[14:15], off offset:1024
	s_waitcnt vmcnt(0)
	v_lshlrev_b32_e32 v18, 16, v32
	v_and_b32_e32 v19, 0xffff0000, v32
	v_lshlrev_b32_e32 v22, 16, v64
	v_and_b32_e32 v23, 0xffff0000, v64
	v_pk_fma_f32 v[18:19], v[4:5], v[22:23], v[18:19]
	v_cvt_pk_bf16_f32 v32, v18, v19
	v_lshlrev_b32_e32 v18, 16, v33
	v_and_b32_e32 v19, 0xffff0000, v33
	v_lshlrev_b32_e32 v22, 16, v65
	v_and_b32_e32 v23, 0xffff0000, v65
	v_pk_fma_f32 v[18:19], v[6:7], v[22:23], v[18:19]
	v_cvt_pk_bf16_f32 v33, v18, v19
	v_lshlrev_b32_e32 v18, 16, v34
	v_and_b32_e32 v19, 0xffff0000, v34
	v_lshlrev_b32_e32 v22, 16, v66
	v_and_b32_e32 v23, 0xffff0000, v66
	v_pk_fma_f32 v[18:19], v[0:1], v[22:23], v[18:19]
	v_cvt_pk_bf16_f32 v34, v18, v19
	v_lshlrev_b32_e32 v18, 16, v35
	v_and_b32_e32 v19, 0xffff0000, v35
	v_lshlrev_b32_e32 v22, 16, v67
	v_and_b32_e32 v23, 0xffff0000, v67
	v_pk_fma_f32 v[18:19], v[2:3], v[22:23], v[18:19]
	v_cvt_pk_bf16_f32 v35, v18, v19
	global_store_dwordx4 v[24:25], v[32:35], off offset:3072
	v_lshl_add_u64 v[24:25], v[24:25], 0, s[0:1]
	v_lshlrev_b32_e32 v18, 16, v36
	v_and_b32_e32 v19, 0xffff0000, v36
	v_lshlrev_b32_e32 v22, 16, v68
	v_and_b32_e32 v23, 0xffff0000, v68
	v_pk_fma_f32 v[18:19], v[4:5], v[22:23], v[18:19]
	v_cvt_pk_bf16_f32 v36, v18, v19
	v_lshlrev_b32_e32 v18, 16, v37
	v_and_b32_e32 v19, 0xffff0000, v37
	v_lshlrev_b32_e32 v22, 16, v69
	v_and_b32_e32 v23, 0xffff0000, v69
	v_pk_fma_f32 v[18:19], v[6:7], v[22:23], v[18:19]
	v_cvt_pk_bf16_f32 v37, v18, v19
	v_lshlrev_b32_e32 v18, 16, v38
	v_and_b32_e32 v19, 0xffff0000, v38
	v_lshlrev_b32_e32 v22, 16, v70
	v_and_b32_e32 v23, 0xffff0000, v70
	v_pk_fma_f32 v[18:19], v[0:1], v[22:23], v[18:19]
	v_cvt_pk_bf16_f32 v38, v18, v19
	v_lshlrev_b32_e32 v18, 16, v39
	v_and_b32_e32 v19, 0xffff0000, v39
	v_lshlrev_b32_e32 v22, 16, v71
	v_and_b32_e32 v23, 0xffff0000, v71
	v_pk_fma_f32 v[18:19], v[2:3], v[22:23], v[18:19]
	v_cvt_pk_bf16_f32 v39, v18, v19
	global_store_dwordx4 v[24:25], v[36:39], off offset:3072
	v_lshl_add_u64 v[24:25], v[24:25], 0, s[0:1]
	v_lshlrev_b32_e32 v18, 16, v40
	v_and_b32_e32 v19, 0xffff0000, v40
	v_lshlrev_b32_e32 v22, 16, v72
	v_and_b32_e32 v23, 0xffff0000, v72
	v_pk_fma_f32 v[18:19], v[4:5], v[22:23], v[18:19]
	v_cvt_pk_bf16_f32 v40, v18, v19
	v_lshlrev_b32_e32 v18, 16, v41
	v_and_b32_e32 v19, 0xffff0000, v41
	v_lshlrev_b32_e32 v22, 16, v73
	v_and_b32_e32 v23, 0xffff0000, v73
	v_pk_fma_f32 v[18:19], v[6:7], v[22:23], v[18:19]
	v_cvt_pk_bf16_f32 v41, v18, v19
	v_lshlrev_b32_e32 v18, 16, v42
	v_and_b32_e32 v19, 0xffff0000, v42
	v_lshlrev_b32_e32 v22, 16, v74
	v_and_b32_e32 v23, 0xffff0000, v74
	v_pk_fma_f32 v[18:19], v[0:1], v[22:23], v[18:19]
	v_cvt_pk_bf16_f32 v42, v18, v19
	v_lshlrev_b32_e32 v18, 16, v43
	v_and_b32_e32 v19, 0xffff0000, v43
	v_lshlrev_b32_e32 v22, 16, v75
	v_and_b32_e32 v23, 0xffff0000, v75
	v_pk_fma_f32 v[18:19], v[2:3], v[22:23], v[18:19]
	v_cvt_pk_bf16_f32 v43, v18, v19
	global_store_dwordx4 v[24:25], v[40:43], off offset:3072
	v_lshl_add_u64 v[24:25], v[24:25], 0, s[0:1]
	v_lshlrev_b32_e32 v18, 16, v44
	v_and_b32_e32 v19, 0xffff0000, v44
	v_lshlrev_b32_e32 v22, 16, v76
	v_and_b32_e32 v23, 0xffff0000, v76
	v_pk_fma_f32 v[18:19], v[4:5], v[22:23], v[18:19]
	v_cvt_pk_bf16_f32 v44, v18, v19
	v_lshlrev_b32_e32 v18, 16, v45
	v_and_b32_e32 v19, 0xffff0000, v45
	v_lshlrev_b32_e32 v22, 16, v77
	v_and_b32_e32 v23, 0xffff0000, v77
	v_pk_fma_f32 v[18:19], v[6:7], v[22:23], v[18:19]
	v_cvt_pk_bf16_f32 v45, v18, v19
	v_lshlrev_b32_e32 v18, 16, v46
	v_and_b32_e32 v19, 0xffff0000, v46
	v_lshlrev_b32_e32 v22, 16, v78
	v_and_b32_e32 v23, 0xffff0000, v78
	v_pk_fma_f32 v[18:19], v[0:1], v[22:23], v[18:19]
	v_cvt_pk_bf16_f32 v46, v18, v19
	v_lshlrev_b32_e32 v18, 16, v47
	v_and_b32_e32 v19, 0xffff0000, v47
	v_lshlrev_b32_e32 v22, 16, v79
	v_and_b32_e32 v23, 0xffff0000, v79
	v_pk_fma_f32 v[18:19], v[2:3], v[22:23], v[18:19]
	v_cvt_pk_bf16_f32 v47, v18, v19
	global_store_dwordx4 v[24:25], v[44:47], off offset:3072
	v_lshl_add_u64 v[24:25], v[24:25], 0, s[0:1]
	v_lshlrev_b32_e32 v18, 16, v48
	v_and_b32_e32 v19, 0xffff0000, v48
	v_lshlrev_b32_e32 v22, 16, v80
	v_and_b32_e32 v23, 0xffff0000, v80
	v_pk_fma_f32 v[18:19], v[4:5], v[22:23], v[18:19]
	v_cvt_pk_bf16_f32 v48, v18, v19
	v_lshlrev_b32_e32 v18, 16, v49
	v_and_b32_e32 v19, 0xffff0000, v49
	v_lshlrev_b32_e32 v22, 16, v81
	v_and_b32_e32 v23, 0xffff0000, v81
	v_pk_fma_f32 v[18:19], v[6:7], v[22:23], v[18:19]
	v_cvt_pk_bf16_f32 v49, v18, v19
	v_lshlrev_b32_e32 v18, 16, v50
	v_and_b32_e32 v19, 0xffff0000, v50
	v_lshlrev_b32_e32 v22, 16, v82
	v_and_b32_e32 v23, 0xffff0000, v82
	v_pk_fma_f32 v[18:19], v[0:1], v[22:23], v[18:19]
	v_cvt_pk_bf16_f32 v50, v18, v19
	v_lshlrev_b32_e32 v18, 16, v51
	v_and_b32_e32 v19, 0xffff0000, v51
	v_lshlrev_b32_e32 v22, 16, v83
	v_and_b32_e32 v23, 0xffff0000, v83
	v_pk_fma_f32 v[18:19], v[2:3], v[22:23], v[18:19]
	v_cvt_pk_bf16_f32 v51, v18, v19
	global_store_dwordx4 v[24:25], v[48:51], off offset:3072
	v_lshl_add_u64 v[24:25], v[24:25], 0, s[0:1]
	v_lshlrev_b32_e32 v18, 16, v52
	v_and_b32_e32 v19, 0xffff0000, v52
	v_lshlrev_b32_e32 v22, 16, v84
	v_and_b32_e32 v23, 0xffff0000, v84
	v_pk_fma_f32 v[18:19], v[4:5], v[22:23], v[18:19]
	v_cvt_pk_bf16_f32 v52, v18, v19
	v_lshlrev_b32_e32 v18, 16, v53
	v_and_b32_e32 v19, 0xffff0000, v53
	v_lshlrev_b32_e32 v22, 16, v85
	v_and_b32_e32 v23, 0xffff0000, v85
	v_pk_fma_f32 v[18:19], v[6:7], v[22:23], v[18:19]
	v_cvt_pk_bf16_f32 v53, v18, v19
	v_lshlrev_b32_e32 v18, 16, v54
	v_and_b32_e32 v19, 0xffff0000, v54
	v_lshlrev_b32_e32 v22, 16, v86
	v_and_b32_e32 v23, 0xffff0000, v86
	v_pk_fma_f32 v[18:19], v[0:1], v[22:23], v[18:19]
	v_cvt_pk_bf16_f32 v54, v18, v19
	v_lshlrev_b32_e32 v18, 16, v55
	v_and_b32_e32 v19, 0xffff0000, v55
	v_lshlrev_b32_e32 v22, 16, v87
	v_and_b32_e32 v23, 0xffff0000, v87
	v_pk_fma_f32 v[18:19], v[2:3], v[22:23], v[18:19]
	v_cvt_pk_bf16_f32 v55, v18, v19
	global_store_dwordx4 v[24:25], v[52:55], off offset:3072
	v_lshl_add_u64 v[24:25], v[24:25], 0, s[0:1]
	v_lshlrev_b32_e32 v18, 16, v56
	v_and_b32_e32 v19, 0xffff0000, v56
	v_lshlrev_b32_e32 v22, 16, v88
	v_and_b32_e32 v23, 0xffff0000, v88
	v_pk_fma_f32 v[18:19], v[4:5], v[22:23], v[18:19]
	v_cvt_pk_bf16_f32 v56, v18, v19
	v_lshlrev_b32_e32 v18, 16, v57
	v_and_b32_e32 v19, 0xffff0000, v57
	v_lshlrev_b32_e32 v22, 16, v89
	v_and_b32_e32 v23, 0xffff0000, v89
	v_pk_fma_f32 v[18:19], v[6:7], v[22:23], v[18:19]
	v_cvt_pk_bf16_f32 v57, v18, v19
	v_lshlrev_b32_e32 v18, 16, v58
	v_and_b32_e32 v19, 0xffff0000, v58
	v_lshlrev_b32_e32 v22, 16, v90
	v_and_b32_e32 v23, 0xffff0000, v90
	v_pk_fma_f32 v[18:19], v[0:1], v[22:23], v[18:19]
	v_cvt_pk_bf16_f32 v58, v18, v19
	v_lshlrev_b32_e32 v18, 16, v59
	v_and_b32_e32 v19, 0xffff0000, v59
	v_lshlrev_b32_e32 v22, 16, v91
	v_and_b32_e32 v23, 0xffff0000, v91
	v_pk_fma_f32 v[18:19], v[2:3], v[22:23], v[18:19]
	v_cvt_pk_bf16_f32 v59, v18, v19
	global_store_dwordx4 v[24:25], v[56:59], off offset:3072
	v_lshl_add_u64 v[24:25], v[24:25], 0, s[0:1]
	v_lshlrev_b32_e32 v18, 16, v60
	v_and_b32_e32 v19, 0xffff0000, v60
	v_lshlrev_b32_e32 v22, 16, v92
	v_and_b32_e32 v23, 0xffff0000, v92
	v_pk_fma_f32 v[18:19], v[4:5], v[22:23], v[18:19]
	v_cvt_pk_bf16_f32 v60, v18, v19
	v_lshlrev_b32_e32 v18, 16, v61
	v_and_b32_e32 v19, 0xffff0000, v61
	v_lshlrev_b32_e32 v22, 16, v93
	v_and_b32_e32 v23, 0xffff0000, v93
	v_pk_fma_f32 v[18:19], v[6:7], v[22:23], v[18:19]
	v_cvt_pk_bf16_f32 v61, v18, v19
	v_lshlrev_b32_e32 v18, 16, v62
	v_and_b32_e32 v19, 0xffff0000, v62
	v_lshlrev_b32_e32 v22, 16, v94
	v_and_b32_e32 v23, 0xffff0000, v94
	v_pk_fma_f32 v[18:19], v[0:1], v[22:23], v[18:19]
	v_cvt_pk_bf16_f32 v62, v18, v19
	v_lshlrev_b32_e32 v18, 16, v63
	v_and_b32_e32 v19, 0xffff0000, v63
	v_lshlrev_b32_e32 v22, 16, v95
	v_and_b32_e32 v23, 0xffff0000, v95
	v_pk_fma_f32 v[18:19], v[2:3], v[22:23], v[18:19]
	v_cvt_pk_bf16_f32 v63, v18, v19
	global_store_dwordx4 v[24:25], v[60:63], off offset:3072
	s_mov_b64 s[0:1], 0
